# OWN attention: partial-output loads 16 bytes per lane (permlane16 swap after the load), halving the combine load count
# speedup vs baseline: 1.0461x; 1.0052x over previous
.LBB0_74:
	v_and_b32_e32 v149, 64, v197
	v_xor_b32_e32 v148, 16, v197
	v_add_u32_e32 v149, 64, v149
	v_cmp_lt_i32_e32 vcc, v148, v149
	s_min_i32 s58, s67, 3
	s_cmp_gt_i32 s67, 0
	v_cndmask_b32_e32 v148, v197, v148, vcc
	v_lshlrev_b32_e32 v152, 2, v148
	ds_bpermute_b32 v150, v152, v190
	v_xor_b32_e32 v148, 32, v197
	v_cmp_lt_i32_e32 vcc, v148, v149
	s_cselect_b64 s[24:25], -1, 0
	s_lshl_b64 s[8:9], s[48:49], 8
	v_cndmask_b32_e32 v148, v197, v148, vcc
	v_lshlrev_b32_e32 v153, 2, v148
	s_waitcnt lgkmcnt(0)
	v_add_f32_e32 v148, v190, v150
	ds_bpermute_b32 v149, v153, v148
	s_cmp_lt_i32 s67, 1
	s_mul_hi_u32 s59, s48, 12
	s_mul_i32 s62, s48, 12
	s_waitcnt lgkmcnt(0)
	v_add_f32_e32 v154, v148, v149
	s_cbranch_scc1 .LBB0_77
	s_add_u32 s68, s43, s62
	s_addc_u32 s69, s47, s59
	v_mov_b64_e32 v[148:149], s[68:69]
	s_movk_i32 s1, 0x60
	v_mad_i64_i32 v[148:149], s[68:69], v232, s1, v[148:149]
	v_mov_b64_e32 v[150:151], s[8:9]
	s_movk_i32 s1, 0x1800
	v_mad_i64_i32 v[150:151], s[68:69], v232, s1, v[150:151]
	v_lshl_add_u64 v[150:151], v[188:189], 0, v[150:151]
	v_and_b32_e32 v254, 16, v197
	v_lshrrev_b32_e32 v155, 1, v254
	v_add_u32_e32 v254, v254, v155
	v_add_co_u32_e32 v150, vcc, v150, v254
	s_nop 1
	v_addc_co_u32_e32 v151, vcc, 0, v151, vcc
	global_load_dword v233, v[148:149], off
	global_load_dwordx4 v[0:3], v[150:151], off offset:-128
	global_load_dwordx4 v[4:7], v[150:151], off offset:-64
	global_load_dwordx4 v[8:11], v[150:151], off offset:0
	global_load_dwordx4 v[12:15], v[150:151], off offset:64
	s_cmp_lt_u32 s58, 2
	s_cbranch_scc1 .Lown_ld0_done
	global_load_dword v234, v[148:149], off offset:4
	global_load_dwordx4 v[16:19], v[150:151], off offset:1920
	global_load_dwordx4 v[20:23], v[150:151], off offset:1984
	global_load_dwordx4 v[24:27], v[150:151], off offset:2048
	global_load_dwordx4 v[28:31], v[150:151], off offset:2112
	s_cmp_lt_u32 s58, 3
	s_cbranch_scc1 .Lown_ld0_done
	global_load_dword v235, v[148:149], off offset:8
	v_add_co_u32_e32 v252, vcc, 0x1000, v150
	s_nop 1
	v_addc_co_u32_e32 v253, vcc, 0, v151, vcc
	global_load_dwordx4 v[236:239], v[252:253], off offset:-128
	global_load_dwordx4 v[240:243], v[252:253], off offset:-64
	global_load_dwordx4 v[244:247], v[252:253], off offset:0
	global_load_dwordx4 v[248:251], v[252:253], off offset:64
.Lown_ld0_done:
	v_add_co_u32_e32 v202, vcc, 0x600, v148
	s_nop 1
	v_addc_co_u32_e32 v203, vcc, 0, v149, vcc
	v_add_co_u32_e32 v204, vcc, 0x18000, v150
	s_nop 1
	v_addc_co_u32_e32 v205, vcc, 0, v151, vcc
	s_waitcnt vmcnt(0)
	v_add_f32_e32 v154, v154, v233
	v_permlane16_swap_b32_e32 v0, v2
	v_permlane16_swap_b32_e32 v1, v3
	v_permlane16_swap_b32_e32 v4, v6
	v_permlane16_swap_b32_e32 v5, v7
	v_permlane16_swap_b32_e32 v8, v10
	v_permlane16_swap_b32_e32 v9, v11
	v_permlane16_swap_b32_e32 v12, v14
	v_permlane16_swap_b32_e32 v13, v15
	v_lshlrev_b32_e32 v254, 16, v0
	v_and_b32_e32 v0, 0xffff0000, v0
	v_lshlrev_b32_e32 v155, 16, v1
	v_and_b32_e32 v1, 0xffff0000, v1
	v_add_f32_e32 v144, v144, v254
	v_add_f32_e32 v145, v145, v0
	v_add_f32_e32 v146, v146, v155
	v_add_f32_e32 v147, v147, v1
	v_lshlrev_b32_e32 v254, 16, v2
	v_and_b32_e32 v2, 0xffff0000, v2
	v_lshlrev_b32_e32 v155, 16, v3
	v_and_b32_e32 v3, 0xffff0000, v3
	v_add_f32_e32 v140, v140, v254
	v_add_f32_e32 v141, v141, v2
	v_add_f32_e32 v142, v142, v155
	v_add_f32_e32 v143, v143, v3
	v_lshlrev_b32_e32 v254, 16, v4
	v_and_b32_e32 v4, 0xffff0000, v4
	v_lshlrev_b32_e32 v155, 16, v5
	v_and_b32_e32 v5, 0xffff0000, v5
	v_add_f32_e32 v136, v136, v254
	v_add_f32_e32 v137, v137, v4
	v_add_f32_e32 v138, v138, v155
	v_add_f32_e32 v139, v139, v5
	v_lshlrev_b32_e32 v254, 16, v6
	v_and_b32_e32 v6, 0xffff0000, v6
	v_lshlrev_b32_e32 v155, 16, v7
	v_and_b32_e32 v7, 0xffff0000, v7
	v_add_f32_e32 v132, v132, v254
	v_add_f32_e32 v133, v133, v6
	v_add_f32_e32 v134, v134, v155
	v_add_f32_e32 v135, v135, v7
	v_lshlrev_b32_e32 v254, 16, v8
	v_and_b32_e32 v8, 0xffff0000, v8
	v_lshlrev_b32_e32 v155, 16, v9
	v_and_b32_e32 v9, 0xffff0000, v9
	v_add_f32_e32 v128, v128, v254
	v_add_f32_e32 v129, v129, v8
	v_add_f32_e32 v130, v130, v155
	v_add_f32_e32 v131, v131, v9
	v_lshlrev_b32_e32 v254, 16, v10
	v_and_b32_e32 v10, 0xffff0000, v10
	v_lshlrev_b32_e32 v155, 16, v11
	v_and_b32_e32 v11, 0xffff0000, v11
	v_add_f32_e32 v124, v124, v254
	v_add_f32_e32 v125, v125, v10
	v_add_f32_e32 v126, v126, v155
	v_add_f32_e32 v127, v127, v11
	v_lshlrev_b32_e32 v254, 16, v12
	v_and_b32_e32 v12, 0xffff0000, v12
	v_lshlrev_b32_e32 v155, 16, v13
	v_and_b32_e32 v13, 0xffff0000, v13
	v_add_f32_e32 v120, v120, v254
	v_add_f32_e32 v121, v121, v12
	v_add_f32_e32 v122, v122, v155
	v_add_f32_e32 v123, v123, v13
	v_lshlrev_b32_e32 v254, 16, v14
	v_and_b32_e32 v14, 0xffff0000, v14
	v_lshlrev_b32_e32 v155, 16, v15
	v_and_b32_e32 v15, 0xffff0000, v15
	v_add_f32_e32 v116, v116, v254
	v_add_f32_e32 v117, v117, v14
	v_add_f32_e32 v118, v118, v155
	v_add_f32_e32 v119, v119, v15
	s_cmp_lt_u32 s58, 2
	s_cbranch_scc1 .Lown_add0_done
	v_add_f32_e32 v154, v154, v234
	v_permlane16_swap_b32_e32 v16, v18
	v_permlane16_swap_b32_e32 v17, v19
	v_permlane16_swap_b32_e32 v20, v22
	v_permlane16_swap_b32_e32 v21, v23
	v_permlane16_swap_b32_e32 v24, v26
	v_permlane16_swap_b32_e32 v25, v27
	v_permlane16_swap_b32_e32 v28, v30
	v_permlane16_swap_b32_e32 v29, v31
	v_lshlrev_b32_e32 v254, 16, v16
	v_and_b32_e32 v16, 0xffff0000, v16
	v_lshlrev_b32_e32 v155, 16, v17
	v_and_b32_e32 v17, 0xffff0000, v17
	v_add_f32_e32 v144, v144, v254
	v_add_f32_e32 v145, v145, v16
	v_add_f32_e32 v146, v146, v155
	v_add_f32_e32 v147, v147, v17
	v_lshlrev_b32_e32 v254, 16, v18
	v_and_b32_e32 v18, 0xffff0000, v18
	v_lshlrev_b32_e32 v155, 16, v19
	v_and_b32_e32 v19, 0xffff0000, v19
	v_add_f32_e32 v140, v140, v254
	v_add_f32_e32 v141, v141, v18
	v_add_f32_e32 v142, v142, v155
	v_add_f32_e32 v143, v143, v19
	v_lshlrev_b32_e32 v254, 16, v20
	v_and_b32_e32 v20, 0xffff0000, v20
	v_lshlrev_b32_e32 v155, 16, v21
	v_and_b32_e32 v21, 0xffff0000, v21
	v_add_f32_e32 v136, v136, v254
	v_add_f32_e32 v137, v137, v20
	v_add_f32_e32 v138, v138, v155
	v_add_f32_e32 v139, v139, v21
	v_lshlrev_b32_e32 v254, 16, v22
	v_and_b32_e32 v22, 0xffff0000, v22
	v_lshlrev_b32_e32 v155, 16, v23
	v_and_b32_e32 v23, 0xffff0000, v23
	v_add_f32_e32 v132, v132, v254
	v_add_f32_e32 v133, v133, v22
	v_add_f32_e32 v134, v134, v155
	v_add_f32_e32 v135, v135, v23
	v_lshlrev_b32_e32 v254, 16, v24
	v_and_b32_e32 v24, 0xffff0000, v24
	v_lshlrev_b32_e32 v155, 16, v25
	v_and_b32_e32 v25, 0xffff0000, v25
	v_add_f32_e32 v128, v128, v254
	v_add_f32_e32 v129, v129, v24
	v_add_f32_e32 v130, v130, v155
	v_add_f32_e32 v131, v131, v25
	v_lshlrev_b32_e32 v254, 16, v26
	v_and_b32_e32 v26, 0xffff0000, v26
	v_lshlrev_b32_e32 v155, 16, v27
	v_and_b32_e32 v27, 0xffff0000, v27
	v_add_f32_e32 v124, v124, v254
	v_add_f32_e32 v125, v125, v26
	v_add_f32_e32 v126, v126, v155
	v_add_f32_e32 v127, v127, v27
	v_lshlrev_b32_e32 v254, 16, v28
	v_and_b32_e32 v28, 0xffff0000, v28
	v_lshlrev_b32_e32 v155, 16, v29
	v_and_b32_e32 v29, 0xffff0000, v29
	v_add_f32_e32 v120, v120, v254
	v_add_f32_e32 v121, v121, v28
	v_add_f32_e32 v122, v122, v155
	v_add_f32_e32 v123, v123, v29
	v_lshlrev_b32_e32 v254, 16, v30
	v_and_b32_e32 v30, 0xffff0000, v30
	v_lshlrev_b32_e32 v155, 16, v31
	v_and_b32_e32 v31, 0xffff0000, v31
	v_add_f32_e32 v116, v116, v254
	v_add_f32_e32 v117, v117, v30
	v_add_f32_e32 v118, v118, v155
	v_add_f32_e32 v119, v119, v31
	s_cmp_lt_u32 s58, 3
	s_cbranch_scc1 .Lown_add0_done
	v_add_f32_e32 v154, v154, v235
	v_permlane16_swap_b32_e32 v236, v238
	v_permlane16_swap_b32_e32 v237, v239
	v_permlane16_swap_b32_e32 v240, v242
	v_permlane16_swap_b32_e32 v241, v243
	v_permlane16_swap_b32_e32 v244, v246
	v_permlane16_swap_b32_e32 v245, v247
	v_permlane16_swap_b32_e32 v248, v250
	v_permlane16_swap_b32_e32 v249, v251
	v_lshlrev_b32_e32 v254, 16, v236
	v_and_b32_e32 v236, 0xffff0000, v236
	v_lshlrev_b32_e32 v155, 16, v237
	v_and_b32_e32 v237, 0xffff0000, v237
	v_add_f32_e32 v144, v144, v254
	v_add_f32_e32 v145, v145, v236
	v_add_f32_e32 v146, v146, v155
	v_add_f32_e32 v147, v147, v237
	v_lshlrev_b32_e32 v254, 16, v238
	v_and_b32_e32 v238, 0xffff0000, v238
	v_lshlrev_b32_e32 v155, 16, v239
	v_and_b32_e32 v239, 0xffff0000, v239
	v_add_f32_e32 v140, v140, v254
	v_add_f32_e32 v141, v141, v238
	v_add_f32_e32 v142, v142, v155
	v_add_f32_e32 v143, v143, v239
	v_lshlrev_b32_e32 v254, 16, v240
	v_and_b32_e32 v240, 0xffff0000, v240
	v_lshlrev_b32_e32 v155, 16, v241
	v_and_b32_e32 v241, 0xffff0000, v241
	v_add_f32_e32 v136, v136, v254
	v_add_f32_e32 v137, v137, v240
	v_add_f32_e32 v138, v138, v155
	v_add_f32_e32 v139, v139, v241
	v_lshlrev_b32_e32 v254, 16, v242
	v_and_b32_e32 v242, 0xffff0000, v242
	v_lshlrev_b32_e32 v155, 16, v243
	v_and_b32_e32 v243, 0xffff0000, v243
	v_add_f32_e32 v132, v132, v254
	v_add_f32_e32 v133, v133, v242
	v_add_f32_e32 v134, v134, v155
	v_add_f32_e32 v135, v135, v243
	v_lshlrev_b32_e32 v254, 16, v244
	v_and_b32_e32 v244, 0xffff0000, v244
	v_lshlrev_b32_e32 v155, 16, v245
	v_and_b32_e32 v245, 0xffff0000, v245
	v_add_f32_e32 v128, v128, v254
	v_add_f32_e32 v129, v129, v244
	v_add_f32_e32 v130, v130, v155
	v_add_f32_e32 v131, v131, v245
	v_lshlrev_b32_e32 v254, 16, v246
	v_and_b32_e32 v246, 0xffff0000, v246
	v_lshlrev_b32_e32 v155, 16, v247
	v_and_b32_e32 v247, 0xffff0000, v247
	v_add_f32_e32 v124, v124, v254
	v_add_f32_e32 v125, v125, v246
	v_add_f32_e32 v126, v126, v155
	v_add_f32_e32 v127, v127, v247
	v_lshlrev_b32_e32 v254, 16, v248
	v_and_b32_e32 v248, 0xffff0000, v248
	v_lshlrev_b32_e32 v155, 16, v249
	v_and_b32_e32 v249, 0xffff0000, v249
	v_add_f32_e32 v120, v120, v254
	v_add_f32_e32 v121, v121, v248
	v_add_f32_e32 v122, v122, v155
	v_add_f32_e32 v123, v123, v249
	v_lshlrev_b32_e32 v254, 16, v250
	v_and_b32_e32 v250, 0xffff0000, v250
	v_lshlrev_b32_e32 v155, 16, v251
	v_and_b32_e32 v251, 0xffff0000, v251
	v_add_f32_e32 v116, v116, v254
	v_add_f32_e32 v117, v117, v250
	v_add_f32_e32 v118, v118, v155
	v_add_f32_e32 v119, v119, v251
.Lown_add0_done:
	global_load_dword v233, v[202:203], off
	global_load_dwordx4 v[0:3], v[204:205], off offset:-128
	global_load_dwordx4 v[4:7], v[204:205], off offset:-64
	global_load_dwordx4 v[8:11], v[204:205], off offset:0
	global_load_dwordx4 v[12:15], v[204:205], off offset:64
	s_cmp_lt_u32 s58, 2
	s_cbranch_scc1 .Lown_ld1_done
	global_load_dword v234, v[202:203], off offset:4
	global_load_dwordx4 v[16:19], v[204:205], off offset:1920
	global_load_dwordx4 v[20:23], v[204:205], off offset:1984
	global_load_dwordx4 v[24:27], v[204:205], off offset:2048
	global_load_dwordx4 v[28:31], v[204:205], off offset:2112
	s_cmp_lt_u32 s58, 3
	s_cbranch_scc1 .Lown_ld1_done
	global_load_dword v235, v[202:203], off offset:8
	v_add_co_u32_e32 v252, vcc, 0x1000, v204
	s_nop 1
	v_addc_co_u32_e32 v253, vcc, 0, v205, vcc
	global_load_dwordx4 v[236:239], v[252:253], off offset:-128
	global_load_dwordx4 v[240:243], v[252:253], off offset:-64
	global_load_dwordx4 v[244:247], v[252:253], off offset:0
	global_load_dwordx4 v[248:251], v[252:253], off offset:64
.Lown_ld1_done:
.LBB0_77:
	v_div_scale_f32 v148, s[68:69], v154, v154, 1.0
	v_rcp_f32_e32 v149, v148
	v_div_scale_f32 v150, vcc, 1.0, v154, 1.0
	v_fma_f32 v151, -v148, v149, 1.0
	v_fmac_f32_e32 v149, v151, v149
	v_mul_f32_e32 v151, v150, v149
	v_fma_f32 v155, -v148, v151, v150
	v_fmac_f32_e32 v151, v155, v149
	v_fma_f32 v148, -v148, v151, v150
	v_div_fmas_f32 v148, v148, v149, v151
	v_div_fixup_f32 v150, v148, v154, 1.0
	v_mad_i64_i32 v[148:149], s[68:69], v232, 24, 0
	v_or_b32_e32 v148, s48, v148
	v_lshlrev_b64 v[148:149], 8, v[148:149]
	v_lshl_add_u64 v[148:149], v[186:187], 0, v[148:149]
	v_and_b32_e32 v151, 16, v197
	v_lshrrev_b32_e32 v155, 1, v151
	v_add_u32_e32 v151, v151, v155
	v_add_co_u32_e32 v148, vcc, v148, v151
	s_nop 1
	v_addc_co_u32_e32 v149, vcc, 0, v149, vcc
	v_mul_f32_e32 v116, v116, v150
	v_mul_f32_e32 v117, v117, v150
	v_mul_f32_e32 v118, v118, v150
	v_mul_f32_e32 v119, v119, v150
	v_mul_f32_e32 v120, v120, v150
	v_mul_f32_e32 v121, v121, v150
	v_mul_f32_e32 v122, v122, v150
	v_mul_f32_e32 v123, v123, v150
	v_mul_f32_e32 v124, v124, v150
	v_mul_f32_e32 v125, v125, v150
	v_mul_f32_e32 v126, v126, v150
	v_mul_f32_e32 v127, v127, v150
	v_mul_f32_e32 v128, v128, v150
	v_mul_f32_e32 v129, v129, v150
	v_mul_f32_e32 v130, v130, v150
	v_mul_f32_e32 v131, v131, v150
	v_mul_f32_e32 v132, v132, v150
	v_mul_f32_e32 v133, v133, v150
	v_mul_f32_e32 v134, v134, v150
	v_mul_f32_e32 v135, v135, v150
	v_mul_f32_e32 v136, v136, v150
	v_mul_f32_e32 v137, v137, v150
	v_mul_f32_e32 v138, v138, v150
	v_mul_f32_e32 v139, v139, v150
	v_mul_f32_e32 v140, v140, v150
	v_mul_f32_e32 v141, v141, v150
	v_mul_f32_e32 v142, v142, v150
	v_mul_f32_e32 v143, v143, v150
	v_mul_f32_e32 v144, v144, v150
	v_mul_f32_e32 v145, v145, v150
	v_mul_f32_e32 v146, v146, v150
	v_mul_f32_e32 v147, v147, v150
	v_cvt_pk_bf16_f32 v144, v144, v145
	v_cvt_pk_bf16_f32 v145, v146, v147
	v_cvt_pk_bf16_f32 v146, v140, v141
	v_cvt_pk_bf16_f32 v147, v142, v143
	v_cvt_pk_bf16_f32 v136, v136, v137
	v_cvt_pk_bf16_f32 v137, v138, v139
	v_cvt_pk_bf16_f32 v138, v132, v133
	v_cvt_pk_bf16_f32 v139, v134, v135
	v_cvt_pk_bf16_f32 v128, v128, v129
	v_cvt_pk_bf16_f32 v129, v130, v131
	v_cvt_pk_bf16_f32 v130, v124, v125
	v_cvt_pk_bf16_f32 v131, v126, v127
	v_cvt_pk_bf16_f32 v119, v118, v119
	v_cvt_pk_bf16_f32 v118, v116, v117
	v_cvt_pk_bf16_f32 v116, v120, v121
	v_cvt_pk_bf16_f32 v117, v122, v123
	s_nop 1
	v_permlane16_swap_b32_e32 v144, v146
	v_permlane16_swap_b32_e32 v145, v147
	v_permlane16_swap_b32_e32 v136, v138
	v_permlane16_swap_b32_e32 v137, v139
	v_permlane16_swap_b32_e32 v128, v130
	v_permlane16_swap_b32_e32 v129, v131
	v_permlane16_swap_b32_e32 v116, v118
	v_permlane16_swap_b32_e32 v117, v119
	global_store_dwordx4 v[148:149], v[144:147], off
	global_store_dwordx4 v[148:149], v[136:139], off offset:64
	global_store_dwordx4 v[148:149], v[128:131], off offset:128
	global_store_dwordx4 v[148:149], v[116:119], off offset:192
	ds_bpermute_b32 v122, v152, v191
	s_and_b64 vcc, exec, s[24:25]
	s_waitcnt lgkmcnt(0)
	v_add_f32_e32 v120, v191, v122
	ds_bpermute_b32 v121, v153, v120
	s_waitcnt lgkmcnt(0)
	v_add_f32_e32 v120, v120, v121
	s_cbranch_vccz .LBB0_64
	s_waitcnt vmcnt(4)
	v_add_f32_e32 v120, v120, v233
	v_permlane16_swap_b32_e32 v0, v2
	v_permlane16_swap_b32_e32 v1, v3
	v_permlane16_swap_b32_e32 v4, v6
	v_permlane16_swap_b32_e32 v5, v7
	v_permlane16_swap_b32_e32 v8, v10
	v_permlane16_swap_b32_e32 v9, v11
	v_permlane16_swap_b32_e32 v12, v14
	v_permlane16_swap_b32_e32 v13, v15
	v_lshlrev_b32_e32 v254, 16, v0
	v_and_b32_e32 v0, 0xffff0000, v0
	v_lshlrev_b32_e32 v155, 16, v1
	v_and_b32_e32 v1, 0xffff0000, v1
	v_add_f32_e32 v112, v112, v254
	v_add_f32_e32 v113, v113, v0
	v_add_f32_e32 v114, v114, v155
	v_add_f32_e32 v115, v115, v1
	v_lshlrev_b32_e32 v254, 16, v2
	v_and_b32_e32 v2, 0xffff0000, v2
	v_lshlrev_b32_e32 v155, 16, v3
	v_and_b32_e32 v3, 0xffff0000, v3
	v_add_f32_e32 v108, v108, v254
	v_add_f32_e32 v109, v109, v2
	v_add_f32_e32 v110, v110, v155
	v_add_f32_e32 v111, v111, v3
	v_lshlrev_b32_e32 v254, 16, v4
	v_and_b32_e32 v4, 0xffff0000, v4
	v_lshlrev_b32_e32 v155, 16, v5
	v_and_b32_e32 v5, 0xffff0000, v5
	v_add_f32_e32 v104, v104, v254
	v_add_f32_e32 v105, v105, v4
	v_add_f32_e32 v106, v106, v155
	v_add_f32_e32 v107, v107, v5
	v_lshlrev_b32_e32 v254, 16, v6
	v_and_b32_e32 v6, 0xffff0000, v6
	v_lshlrev_b32_e32 v155, 16, v7
	v_and_b32_e32 v7, 0xffff0000, v7
	v_add_f32_e32 v100, v100, v254
	v_add_f32_e32 v101, v101, v6
	v_add_f32_e32 v102, v102, v155
	v_add_f32_e32 v103, v103, v7
	v_lshlrev_b32_e32 v254, 16, v8
	v_and_b32_e32 v8, 0xffff0000, v8
	v_lshlrev_b32_e32 v155, 16, v9
	v_and_b32_e32 v9, 0xffff0000, v9
	v_add_f32_e32 v96, v96, v254
	v_add_f32_e32 v97, v97, v8
	v_add_f32_e32 v98, v98, v155
	v_add_f32_e32 v99, v99, v9
	v_lshlrev_b32_e32 v254, 16, v10
	v_and_b32_e32 v10, 0xffff0000, v10
	v_lshlrev_b32_e32 v155, 16, v11
	v_and_b32_e32 v11, 0xffff0000, v11
	v_add_f32_e32 v92, v92, v254
	v_add_f32_e32 v93, v93, v10
	v_add_f32_e32 v94, v94, v155
	v_add_f32_e32 v95, v95, v11
	v_lshlrev_b32_e32 v254, 16, v12
	v_and_b32_e32 v12, 0xffff0000, v12
	v_lshlrev_b32_e32 v155, 16, v13
	v_and_b32_e32 v13, 0xffff0000, v13
	v_add_f32_e32 v88, v88, v254
	v_add_f32_e32 v89, v89, v12
	v_add_f32_e32 v90, v90, v155
	v_add_f32_e32 v91, v91, v13
	v_lshlrev_b32_e32 v254, 16, v14
	v_and_b32_e32 v14, 0xffff0000, v14
	v_lshlrev_b32_e32 v155, 16, v15
	v_and_b32_e32 v15, 0xffff0000, v15
	v_add_f32_e32 v84, v84, v254
	v_add_f32_e32 v85, v85, v14
	v_add_f32_e32 v86, v86, v155
	v_add_f32_e32 v87, v87, v15
	s_cmp_lt_u32 s58, 2
	s_cbranch_scc1 .Lown_add1_done
	v_add_f32_e32 v120, v120, v234
	v_permlane16_swap_b32_e32 v16, v18
	v_permlane16_swap_b32_e32 v17, v19
	v_permlane16_swap_b32_e32 v20, v22
	v_permlane16_swap_b32_e32 v21, v23
	v_permlane16_swap_b32_e32 v24, v26
	v_permlane16_swap_b32_e32 v25, v27
	v_permlane16_swap_b32_e32 v28, v30
	v_permlane16_swap_b32_e32 v29, v31
	v_lshlrev_b32_e32 v254, 16, v16
	v_and_b32_e32 v16, 0xffff0000, v16
	v_lshlrev_b32_e32 v155, 16, v17
	v_and_b32_e32 v17, 0xffff0000, v17
	v_add_f32_e32 v112, v112, v254
	v_add_f32_e32 v113, v113, v16
	v_add_f32_e32 v114, v114, v155
	v_add_f32_e32 v115, v115, v17
	v_lshlrev_b32_e32 v254, 16, v18
	v_and_b32_e32 v18, 0xffff0000, v18
	v_lshlrev_b32_e32 v155, 16, v19
	v_and_b32_e32 v19, 0xffff0000, v19
	v_add_f32_e32 v108, v108, v254
	v_add_f32_e32 v109, v109, v18
	v_add_f32_e32 v110, v110, v155
	v_add_f32_e32 v111, v111, v19
	v_lshlrev_b32_e32 v254, 16, v20
	v_and_b32_e32 v20, 0xffff0000, v20
	v_lshlrev_b32_e32 v155, 16, v21
	v_and_b32_e32 v21, 0xffff0000, v21
	v_add_f32_e32 v104, v104, v254
	v_add_f32_e32 v105, v105, v20
	v_add_f32_e32 v106, v106, v155
	v_add_f32_e32 v107, v107, v21
	v_lshlrev_b32_e32 v254, 16, v22
	v_and_b32_e32 v22, 0xffff0000, v22
	v_lshlrev_b32_e32 v155, 16, v23
	v_and_b32_e32 v23, 0xffff0000, v23
	v_add_f32_e32 v100, v100, v254
	v_add_f32_e32 v101, v101, v22
	v_add_f32_e32 v102, v102, v155
	v_add_f32_e32 v103, v103, v23
	v_lshlrev_b32_e32 v254, 16, v24
	v_and_b32_e32 v24, 0xffff0000, v24
	v_lshlrev_b32_e32 v155, 16, v25
	v_and_b32_e32 v25, 0xffff0000, v25
	v_add_f32_e32 v96, v96, v254
	v_add_f32_e32 v97, v97, v24
	v_add_f32_e32 v98, v98, v155
	v_add_f32_e32 v99, v99, v25
	v_lshlrev_b32_e32 v254, 16, v26
	v_and_b32_e32 v26, 0xffff0000, v26
	v_lshlrev_b32_e32 v155, 16, v27
	v_and_b32_e32 v27, 0xffff0000, v27
	v_add_f32_e32 v92, v92, v254
	v_add_f32_e32 v93, v93, v26
	v_add_f32_e32 v94, v94, v155
	v_add_f32_e32 v95, v95, v27
	v_lshlrev_b32_e32 v254, 16, v28
	v_and_b32_e32 v28, 0xffff0000, v28
	v_lshlrev_b32_e32 v155, 16, v29
	v_and_b32_e32 v29, 0xffff0000, v29
	v_add_f32_e32 v88, v88, v254
	v_add_f32_e32 v89, v89, v28
	v_add_f32_e32 v90, v90, v155
	v_add_f32_e32 v91, v91, v29
	v_lshlrev_b32_e32 v254, 16, v30
	v_and_b32_e32 v30, 0xffff0000, v30
	v_lshlrev_b32_e32 v155, 16, v31
	v_and_b32_e32 v31, 0xffff0000, v31
	v_add_f32_e32 v84, v84, v254
	v_add_f32_e32 v85, v85, v30
	v_add_f32_e32 v86, v86, v155
	v_add_f32_e32 v87, v87, v31
	s_cmp_lt_u32 s58, 3
	s_cbranch_scc1 .Lown_add1_done
	v_add_f32_e32 v120, v120, v235
	v_permlane16_swap_b32_e32 v236, v238
	v_permlane16_swap_b32_e32 v237, v239
	v_permlane16_swap_b32_e32 v240, v242
	v_permlane16_swap_b32_e32 v241, v243
	v_permlane16_swap_b32_e32 v244, v246
	v_permlane16_swap_b32_e32 v245, v247
	v_permlane16_swap_b32_e32 v248, v250
	v_permlane16_swap_b32_e32 v249, v251
	v_lshlrev_b32_e32 v254, 16, v236
	v_and_b32_e32 v236, 0xffff0000, v236
	v_lshlrev_b32_e32 v155, 16, v237
	v_and_b32_e32 v237, 0xffff0000, v237
	v_add_f32_e32 v112, v112, v254
	v_add_f32_e32 v113, v113, v236
	v_add_f32_e32 v114, v114, v155
	v_add_f32_e32 v115, v115, v237
	v_lshlrev_b32_e32 v254, 16, v238
	v_and_b32_e32 v238, 0xffff0000, v238
	v_lshlrev_b32_e32 v155, 16, v239
	v_and_b32_e32 v239, 0xffff0000, v239
	v_add_f32_e32 v108, v108, v254
	v_add_f32_e32 v109, v109, v238
	v_add_f32_e32 v110, v110, v155
	v_add_f32_e32 v111, v111, v239
	v_lshlrev_b32_e32 v254, 16, v240
	v_and_b32_e32 v240, 0xffff0000, v240
	v_lshlrev_b32_e32 v155, 16, v241
	v_and_b32_e32 v241, 0xffff0000, v241
	v_add_f32_e32 v104, v104, v254
	v_add_f32_e32 v105, v105, v240
	v_add_f32_e32 v106, v106, v155
	v_add_f32_e32 v107, v107, v241
	v_lshlrev_b32_e32 v254, 16, v242
	v_and_b32_e32 v242, 0xffff0000, v242
	v_lshlrev_b32_e32 v155, 16, v243
	v_and_b32_e32 v243, 0xffff0000, v243
	v_add_f32_e32 v100, v100, v254
	v_add_f32_e32 v101, v101, v242
	v_add_f32_e32 v102, v102, v155
	v_add_f32_e32 v103, v103, v243
	v_lshlrev_b32_e32 v254, 16, v244
	v_and_b32_e32 v244, 0xffff0000, v244
	v_lshlrev_b32_e32 v155, 16, v245
	v_and_b32_e32 v245, 0xffff0000, v245
	v_add_f32_e32 v96, v96, v254
	v_add_f32_e32 v97, v97, v244
	v_add_f32_e32 v98, v98, v155
	v_add_f32_e32 v99, v99, v245
	v_lshlrev_b32_e32 v254, 16, v246
	v_and_b32_e32 v246, 0xffff0000, v246
	v_lshlrev_b32_e32 v155, 16, v247
	v_and_b32_e32 v247, 0xffff0000, v247
	v_add_f32_e32 v92, v92, v254
	v_add_f32_e32 v93, v93, v246
	v_add_f32_e32 v94, v94, v155
	v_add_f32_e32 v95, v95, v247
	v_lshlrev_b32_e32 v254, 16, v248
	v_and_b32_e32 v248, 0xffff0000, v248
	v_lshlrev_b32_e32 v155, 16, v249
	v_and_b32_e32 v249, 0xffff0000, v249
	v_add_f32_e32 v88, v88, v254
	v_add_f32_e32 v89, v89, v248
	v_add_f32_e32 v90, v90, v155
	v_add_f32_e32 v91, v91, v249
	v_lshlrev_b32_e32 v254, 16, v250
	v_and_b32_e32 v250, 0xffff0000, v250
	v_lshlrev_b32_e32 v155, 16, v251
	v_and_b32_e32 v251, 0xffff0000, v251
	v_add_f32_e32 v84, v84, v254
	v_add_f32_e32 v85, v85, v250
	v_add_f32_e32 v86, v86, v155
	v_add_f32_e32 v87, v87, v251
